# grid barrier: waiting workgroups poll the top-level generation word directly instead of their XCD's word (one hop less on release)
# speedup vs baseline: 1.0077x; 1.0052x over previous
.LBB0_31:
	s_or_b64 exec, exec, s[2:3]
	v_cvt_f32_u32_e32 v5, v3
	s_waitcnt vmcnt(0)
	v_readfirstlane_b32 s2, v4
	v_sub_u32_e32 v4, 0, v3
	v_rcp_iflag_f32_e32 v5, v5
	v_add_u32_e32 v6, s2, v0
	v_mul_f32_e32 v5, 0x4f7ffffe, v5
	v_cvt_u32_f32_e32 v5, v5
	v_mul_lo_u32 v0, v4, v5
	v_mul_hi_u32 v0, v5, v0
	v_add_u32_e32 v0, v5, v0
	v_mul_hi_u32 v0, v6, v0
	v_mul_lo_u32 v4, v0, v3
	v_sub_u32_e32 v4, v6, v4
	v_add_u32_e32 v5, 1, v0
	v_cmp_ge_u32_e32 vcc, v4, v3
	s_nop 1
	v_cndmask_b32_e32 v0, v0, v5, vcc
	v_sub_u32_e32 v5, v4, v3
	v_cndmask_b32_e32 v4, v4, v5, vcc
	v_add_u32_e32 v5, 1, v0
	v_cmp_ge_u32_e32 vcc, v4, v3
	v_add_u32_e32 v4, 1, v6
	s_nop 0
	v_cndmask_b32_e32 v0, v0, v5, vcc
	v_mul_lo_u32 v5, v3, v0
	v_add_u32_e32 v3, v5, v3
	v_cmp_ne_u32_e32 vcc, v4, v3
	s_and_saveexec_b64 s[2:3], vcc
	s_xor_b64 s[2:3], exec, s[2:3]
	s_cbranch_execz .LBB0_45
	v_readlane_b32 s8, v254, 51
	v_readlane_b32 s9, v254, 52
	s_waitcnt lgkmcnt(0)
	s_nop 3
	global_load_dword v2, v1, s[8:9] sc1
	s_waitcnt vmcnt(0)
	v_cmp_eq_u32_e32 vcc, v2, v0
	s_and_saveexec_b64 s[8:9], vcc
	s_cbranch_execz .LBB0_44
	s_mov_b32 s24, 1
	s_mov_b64 s[10:11], 0
	s_branch .LBB0_35

.LBB0_351:
	s_or_b64 exec, exec, s[10:11]
	v_cvt_f32_u32_e32 v5, v3
	s_waitcnt vmcnt(0)
	v_readfirstlane_b32 s10, v4
	v_sub_u32_e32 v4, 0, v3
	v_rcp_iflag_f32_e32 v5, v5
	v_add_u32_e32 v6, s10, v0
	v_mul_f32_e32 v5, 0x4f7ffffe, v5
	v_cvt_u32_f32_e32 v5, v5
	v_mul_lo_u32 v0, v4, v5
	v_mul_hi_u32 v0, v5, v0
	v_add_u32_e32 v0, v5, v0
	v_mul_hi_u32 v0, v6, v0
	v_mul_lo_u32 v4, v0, v3
	v_sub_u32_e32 v4, v6, v4
	v_add_u32_e32 v5, 1, v0
	v_cmp_ge_u32_e32 vcc, v4, v3
	s_nop 1
	v_cndmask_b32_e32 v0, v0, v5, vcc
	v_sub_u32_e32 v5, v4, v3
	v_cndmask_b32_e32 v4, v4, v5, vcc
	v_add_u32_e32 v5, 1, v0
	v_cmp_ge_u32_e32 vcc, v4, v3
	v_add_u32_e32 v4, 1, v6
	s_nop 0
	v_cndmask_b32_e32 v0, v0, v5, vcc
	v_mul_lo_u32 v5, v3, v0
	v_add_u32_e32 v3, v5, v3
	v_cmp_ne_u32_e32 vcc, v4, v3
	s_and_saveexec_b64 s[10:11], vcc
	s_xor_b64 s[10:11], exec, s[10:11]
	s_cbranch_execz .LBB0_365
	v_readlane_b32 s14, v254, 51
	v_readlane_b32 s15, v254, 52
	s_waitcnt lgkmcnt(0)
	s_nop 3
	global_load_dword v2, v1, s[14:15] sc1
	s_waitcnt vmcnt(0)
	v_cmp_eq_u32_e32 vcc, v2, v0
	s_and_saveexec_b64 s[14:15], vcc
	s_cbranch_execz .LBB0_364
	s_mov_b32 s60, 1
	s_mov_b64 s[18:19], 0
	s_branch .LBB0_355
